# in-projection GEMM K-loop: ten LDS-DMA sites switched to SGPR-base addressing, six 64-bit VALU address adds removed
# baseline (speedup 1.0000x reference)
; #define PG8_STAGE(bufoff, gbase, voff) do { _Pragma("unroll") for (int _i = 0; _i < 2; ++_i) \
;         __builtin_amdgcn_global_load_lds((const unsigned*)((const char*)(gbase) + (voff)[_i]), (PG8_LAS unsigned*)(lds + (bufoff) + ldsw + _i * 8192), 16, 0, 0); } while (0)
; #define PG8_LDA(dst, b, h) do { _Pragma("unroll") for (int m = 0; m < 4; ++m) _Pragma("unroll") for (int k = 0; k < 2; ++k) dst[m][k] = *(const PG8_LAS bf16x8*)(lds + PG8_SA(b, h) + aoff + m * 2048 + k * 1024); } while (0)
; #define PG8_LDB(dst, b, h) do { _Pragma("unroll") for (int n = 0; n < 2; ++n) _Pragma("unroll") for (int k = 0; k < 2; ++k) dst[n][k] = *(const PG8_LAS bf16x8*)(lds + PG8_SB(b, h) + boff + n * 2048 + k * 1024); } while (0)
; #define PG8_MMA(ai, bj, At, Bt) do { __builtin_amdgcn_s_setprio(1); _Pragma("unroll") for (int m = 0; m < 4; ++m) _Pragma("unroll") for (int n = 0; n < 2; ++n) _Pragma("unroll") for (int k = 0; k < 2; ++k) \
;         acc[ai][bj][m][n] = __builtin_amdgcn_mfma_f32_16x16x32_bf16(Bt[n][k], At[m][k], acc[ai][bj][m][n], 0, 0, 0); __builtin_amdgcn_s_setprio(0); } while (0)
; #define PG8_WAIT_V(n) asm volatile("s_waitcnt vmcnt(" #n ")" ::: "memory")
; #define PG8_WAIT_L(n) asm volatile("s_waitcnt lgkmcnt(" #n ")" ::: "memory")
; #define PG8_BAR __builtin_amdgcn_s_barrier()
; #define PG8_SCHED __builtin_amdgcn_sched_barrier(0)
; #define PG8_STAGE(bufoff, gbase, voff) do { _Pragma("unroll") for (int _i = 0; _i < 2; ++_i) \
;         __builtin_amdgcn_global_load_lds((const unsigned*)((const char*)(gbase) + (voff)[_i]), (PG8_LAS unsigned*)(lds + (bufoff) + ldsw + _i * 8192), 16, 0, 0); } while (0)
; #define PG8_BAR __builtin_amdgcn_s_barrier()
; template <class Epi, class Sched, bool ALIGN_EPI = false, bool SP2 = false>
; __device__ __forceinline__ void gemm_phase(PG8_LAS unsigned char* lds, const Gemm g, const Sched& S, const Epi& E, const int tid_in) {
;     ...
;             PG8_LDB(B0, 0, 0); PG8_LDB(B1, 0, 1); PG8_SCHED; PG8_LDA(At, 0, 0); PG8_STAGE(PG8_SA(1, 1), a1 + hstep, voffA);
;             PG8_WAIT_V(8); PG8_WAIT_L(0); PG8_BAR; PG8_MMA(0, 0, At, B0); PG8_MMA(0, 1, At, B1); PG8_BAR; PG8_SCHED;
;             PG8_LDA(At, 0, 1); PG8_STAGE(PG8_SB(0, 0), b2, voffB); PG8_STAGE(PG8_SB(0, 1), b2 + hstep, voffB); PG8_STAGE(PG8_SA(0, 0), a2, voffA);
;             PG8_WAIT_V(8); PG8_WAIT_L(0); PG8_BAR; PG8_MMA(1, 0, At, B0); PG8_MMA(1, 1, At, B1); PG8_BAR; PG8_SCHED;
.LBB0_221:
	s_add_u32 s14, s8, 0xfffc0080
	s_addc_u32 s15, s9, -1
	s_add_i32 s68, 0, 0x10000
	s_cmp_eq_u32 vcc_hi, 12
	s_cselect_b32 s55, s11, s15
	s_cselect_b32 s54, s80, s14
	v_add_u32_e32 v0, s68, v141
	s_cselect_b32 s15, s35, vcc_lo
	s_cselect_b32 s14, s89, s91
	s_add_i32 s51, 0, 0x14000
	ds_read_b128 v[150:153], v0
	ds_read_b128 v[154:157], v0 offset:1024
	ds_read_b128 v[172:175], v0 offset:2048
	ds_read_b128 v[176:179], v0 offset:3072
	v_add_u32_e32 v0, s51, v141
	ds_read_b128 v[180:183], v0
	ds_read_b128 v[184:187], v0 offset:1024
	ds_read_b128 v[188:191], v0 offset:2048
	ds_read_b128 v[202:205], v0 offset:3072
	v_lshl_add_u64 v[238:239], s[8:9], 0, v[146:147]
	s_add_i32 m0, s45, 0xc000
	ds_read_b128 v[206:209], v159
	ds_read_b128 v[210:213], v159 offset:1024
	ds_read_b128 v[214:217], v159 offset:2048
	ds_read_b128 v[218:221], v159 offset:3072
	ds_read_b128 v[222:225], v159 offset:4096
	ds_read_b128 v[226:229], v159 offset:5120
	ds_read_b128 v[230:233], v159 offset:6144
	ds_read_b128 v[234:237], v159 offset:7168
	global_load_lds_dwordx4 v[238:239], off
	v_lshl_add_u64 v[238:239], s[8:9], 0, v[148:149]
	s_add_i32 m0, s45, 0xe000
	s_nop 0
	global_load_lds_dwordx4 v[238:239], off
	s_waitcnt vmcnt(8)
	s_waitcnt lgkmcnt(0)
	s_barrier
	s_setprio 1
	s_waitcnt lgkmcnt(0)
	v_mfma_f32_16x16x32_bf16 v[126:129], v[150:153], v[206:209], v[126:129]
	v_mfma_f32_16x16x32_bf16 v[118:121], v[172:175], v[206:209], v[118:121]
	v_mfma_f32_16x16x32_bf16 v[110:113], v[150:153], v[214:217], v[110:113]
	v_mfma_f32_16x16x32_bf16 v[102:105], v[172:175], v[214:217], v[102:105]
	v_mfma_f32_16x16x32_bf16 v[94:97], v[150:153], v[222:225], v[94:97]
	v_mfma_f32_16x16x32_bf16 v[86:89], v[172:175], v[222:225], v[86:89]
	v_mfma_f32_16x16x32_bf16 v[78:81], v[150:153], v[230:233], v[78:81]
	v_mfma_f32_16x16x32_bf16 v[70:73], v[172:175], v[230:233], v[70:73]
	v_mfma_f32_16x16x32_bf16 v[126:129], v[154:157], v[210:213], v[126:129]
	v_mfma_f32_16x16x32_bf16 v[118:121], v[176:179], v[210:213], v[118:121]
	v_mfma_f32_16x16x32_bf16 v[110:113], v[154:157], v[218:221], v[110:113]
	v_mfma_f32_16x16x32_bf16 v[102:105], v[176:179], v[218:221], v[102:105]
	v_mfma_f32_16x16x32_bf16 v[94:97], v[154:157], v[226:229], v[94:97]
	v_mfma_f32_16x16x32_bf16 v[86:89], v[176:179], v[226:229], v[86:89]
	v_mfma_f32_16x16x32_bf16 v[78:81], v[154:157], v[234:237], v[78:81]
	v_mfma_f32_16x16x32_bf16 v[70:73], v[176:179], v[234:237], v[70:73]
	s_setprio 0
	s_setprio 1
	v_mfma_f32_16x16x32_bf16 v[122:125], v[180:183], v[206:209], v[122:125]
	v_mfma_f32_16x16x32_bf16 v[114:117], v[188:191], v[206:209], v[114:117]
	v_mfma_f32_16x16x32_bf16 v[106:109], v[180:183], v[214:217], v[106:109]
	v_mfma_f32_16x16x32_bf16 v[98:101], v[188:191], v[214:217], v[98:101]
	v_mfma_f32_16x16x32_bf16 v[90:93], v[180:183], v[222:225], v[90:93]
	v_mfma_f32_16x16x32_bf16 v[82:85], v[188:191], v[222:225], v[82:85]
	v_mfma_f32_16x16x32_bf16 v[74:77], v[180:183], v[230:233], v[74:77]
	v_mfma_f32_16x16x32_bf16 v[66:69], v[188:191], v[230:233], v[66:69]
	v_mfma_f32_16x16x32_bf16 v[122:125], v[184:187], v[210:213], v[122:125]
	v_mfma_f32_16x16x32_bf16 v[114:117], v[202:205], v[210:213], v[114:117]
	v_mfma_f32_16x16x32_bf16 v[106:109], v[184:187], v[218:221], v[106:109]
	v_mfma_f32_16x16x32_bf16 v[98:101], v[202:205], v[218:221], v[98:101]
	v_mfma_f32_16x16x32_bf16 v[90:93], v[184:187], v[226:229], v[90:93]
	v_mfma_f32_16x16x32_bf16 v[82:85], v[202:205], v[226:229], v[82:85]
	v_mfma_f32_16x16x32_bf16 v[74:77], v[184:187], v[234:237], v[74:77]
	v_mfma_f32_16x16x32_bf16 v[66:69], v[202:205], v[234:237], v[66:69]
	s_setprio 0
	s_barrier
	s_add_i32 s68, s68, s44
	v_lshl_add_u64 v[238:239], s[14:15], 0, v[132:133]
	s_mov_b32 m0, s68
	ds_read_b128 v[206:209], v159 offset:16384
	ds_read_b128 v[210:213], v159 offset:17408
	ds_read_b128 v[214:217], v159 offset:18432
	ds_read_b128 v[218:221], v159 offset:19456
	ds_read_b128 v[222:225], v159 offset:20480
	ds_read_b128 v[226:229], v159 offset:21504
	ds_read_b128 v[230:233], v159 offset:22528
	ds_read_b128 v[234:237], v159 offset:23552
	global_load_lds_dwordx4 v132, s[14:15]
	s_add_i32 m0, s68, 0x2000
	s_add_u32 s68, s14, 0x40000
	v_lshl_add_u64 v[240:241], s[14:15], 0, v[136:137]
	s_addc_u32 s69, s15, 0
	s_add_i32 s51, s51, s44
	global_load_lds_dwordx4 v136, s[14:15]
	s_mov_b32 m0, s51
	v_lshl_add_u64 v[244:245], s[54:55], 0, v[134:135]
	global_load_lds_dwordx4 v132, s[68:69]
	s_add_i32 m0, s51, 0x2000
	s_nop 0
	global_load_lds_dwordx4 v136, s[68:69]
	v_lshl_add_u64 v[242:243], s[54:55], 0, v[130:131]
	s_mov_b32 m0, s45
	s_nop 0
	global_load_lds_dwordx4 v130, s[54:55]
	s_mov_b32 m0, s47
	s_nop 0
	global_load_lds_dwordx4 v134, s[54:55]
	s_waitcnt vmcnt(8)
	s_waitcnt lgkmcnt(0)
	s_barrier
; #define PG8_STAGE(bufoff, gbase, voff) do { _Pragma("unroll") for (int _i = 0; _i < 2; ++_i) \
;         __builtin_amdgcn_global_load_lds((const unsigned*)((const char*)(gbase) + (voff)[_i]), (PG8_LAS unsigned*)(lds + (bufoff) + ldsw + _i * 8192), 16, 0, 0); } while (0)
; #define PG8_LDA(dst, b, h) do { _Pragma("unroll") for (int m = 0; m < 4; ++m) _Pragma("unroll") for (int k = 0; k < 2; ++k) dst[m][k] = *(const PG8_LAS bf16x8*)(lds + PG8_SA(b, h) + aoff + m * 2048 + k * 1024); } while (0)
; #define PG8_LDB(dst, b, h) do { _Pragma("unroll") for (int n = 0; n < 2; ++n) _Pragma("unroll") for (int k = 0; k < 2; ++k) dst[n][k] = *(const PG8_LAS bf16x8*)(lds + PG8_SB(b, h) + boff + n * 2048 + k * 1024); } while (0)
; #define PG8_MMA(ai, bj, At, Bt) do { __builtin_amdgcn_s_setprio(1); _Pragma("unroll") for (int m = 0; m < 4; ++m) _Pragma("unroll") for (int n = 0; n < 2; ++n) _Pragma("unroll") for (int k = 0; k < 2; ++k) \
;         acc[ai][bj][m][n] = __builtin_amdgcn_mfma_f32_16x16x32_bf16(Bt[n][k], At[m][k], acc[ai][bj][m][n], 0, 0, 0); __builtin_amdgcn_s_setprio(0); } while (0)
; #define PG8_WAIT_V(n) asm volatile("s_waitcnt vmcnt(" #n ")" ::: "memory")
; #define PG8_WAIT_L(n) asm volatile("s_waitcnt lgkmcnt(" #n ")" ::: "memory")
; #define PG8_BAR __builtin_amdgcn_s_barrier()
; #define PG8_SCHED __builtin_amdgcn_sched_barrier(0)
; #define PG8_STAGE(bufoff, gbase, voff) do { _Pragma("unroll") for (int _i = 0; _i < 2; ++_i) \
;         __builtin_amdgcn_global_load_lds((const unsigned*)((const char*)(gbase) + (voff)[_i]), (PG8_LAS unsigned*)(lds + (bufoff) + ldsw + _i * 8192), 16, 0, 0); } while (0)
; #define PG8_WAIT_V(n) asm volatile("s_waitcnt vmcnt(" #n ")" ::: "memory")
; #define PG8_WAIT_L(n) asm volatile("s_waitcnt lgkmcnt(" #n ")" ::: "memory")
; template <class Epi, class Sched, bool ALIGN_EPI = false, bool SP2 = false>
; __device__ __forceinline__ void gemm_phase(PG8_LAS unsigned char* lds, const Gemm g, const Sched& S, const Epi& E, const int tid_in) {
;     ...
;             PG8_WAIT_V(8); PG8_WAIT_L(0); PG8_BAR; PG8_MMA(1, 0, At, B0); PG8_MMA(1, 1, At, B1); PG8_BAR; PG8_SCHED;
;             PG8_LDB(B0, 1, 0); PG8_LDB(B1, 1, 1); PG8_SCHED; PG8_LDA(At, 1, 0); PG8_STAGE(PG8_SA(0, 1), a2 + hstep, voffA);
;             PG8_WAIT_V(8); PG8_WAIT_L(0); PG8_BAR; PG8_MMA(0, 0, At, B0); PG8_MMA(0, 1, At, B1); PG8_BAR; PG8_SCHED;
	s_setprio 1
	s_waitcnt lgkmcnt(0)
	v_mfma_f32_16x16x32_bf16 v[62:65], v[150:153], v[206:209], v[62:65]
	v_mfma_f32_16x16x32_bf16 v[54:57], v[172:175], v[206:209], v[54:57]
	v_mfma_f32_16x16x32_bf16 v[46:49], v[150:153], v[214:217], v[46:49]
	v_mfma_f32_16x16x32_bf16 v[38:41], v[172:175], v[214:217], v[38:41]
	v_mfma_f32_16x16x32_bf16 v[30:33], v[150:153], v[222:225], v[30:33]
	v_mfma_f32_16x16x32_bf16 v[22:25], v[172:175], v[222:225], v[22:25]
	v_mfma_f32_16x16x32_bf16 v[14:17], v[150:153], v[230:233], v[14:17]
	v_mfma_f32_16x16x32_bf16 v[6:9], v[172:175], v[230:233], v[6:9]
	v_mfma_f32_16x16x32_bf16 v[62:65], v[154:157], v[210:213], v[62:65]
	v_mfma_f32_16x16x32_bf16 v[54:57], v[176:179], v[210:213], v[54:57]
	v_mfma_f32_16x16x32_bf16 v[46:49], v[154:157], v[218:221], v[46:49]
	v_mfma_f32_16x16x32_bf16 v[38:41], v[176:179], v[218:221], v[38:41]
	v_mfma_f32_16x16x32_bf16 v[30:33], v[154:157], v[226:229], v[30:33]
	v_mfma_f32_16x16x32_bf16 v[22:25], v[176:179], v[226:229], v[22:25]
	v_mfma_f32_16x16x32_bf16 v[14:17], v[154:157], v[234:237], v[14:17]
	v_mfma_f32_16x16x32_bf16 v[6:9], v[176:179], v[234:237], v[6:9]
	s_setprio 0
	s_setprio 1
	v_mfma_f32_16x16x32_bf16 v[58:61], v[180:183], v[206:209], v[58:61]
	v_mfma_f32_16x16x32_bf16 v[50:53], v[188:191], v[206:209], v[50:53]
	v_mfma_f32_16x16x32_bf16 v[42:45], v[180:183], v[214:217], v[42:45]
	v_mfma_f32_16x16x32_bf16 v[34:37], v[188:191], v[214:217], v[34:37]
	v_mfma_f32_16x16x32_bf16 v[26:29], v[180:183], v[222:225], v[26:29]
	v_mfma_f32_16x16x32_bf16 v[18:21], v[188:191], v[222:225], v[18:21]
	v_mfma_f32_16x16x32_bf16 v[10:13], v[180:183], v[230:233], v[10:13]
	v_mfma_f32_16x16x32_bf16 v[2:5], v[188:191], v[230:233], v[2:5]
	v_mfma_f32_16x16x32_bf16 v[58:61], v[184:187], v[210:213], v[58:61]
	v_mfma_f32_16x16x32_bf16 v[50:53], v[202:205], v[210:213], v[50:53]
	v_mfma_f32_16x16x32_bf16 v[42:45], v[184:187], v[218:221], v[42:45]
	v_mfma_f32_16x16x32_bf16 v[34:37], v[202:205], v[218:221], v[34:37]
	v_mfma_f32_16x16x32_bf16 v[26:29], v[184:187], v[226:229], v[26:29]
	v_mfma_f32_16x16x32_bf16 v[18:21], v[202:205], v[226:229], v[18:21]
	v_mfma_f32_16x16x32_bf16 v[10:13], v[184:187], v[234:237], v[10:13]
	v_mfma_f32_16x16x32_bf16 v[2:5], v[202:205], v[234:237], v[2:5]
	s_setprio 0
	s_barrier
	s_add_i32 s51, 0, 0x18000
	v_add_u32_e32 v0, s51, v141
	s_add_i32 s68, 0, 0x1c000
	ds_read_b128 v[150:153], v0
	ds_read_b128 v[154:157], v0 offset:1024
	ds_read_b128 v[172:175], v0 offset:2048
	ds_read_b128 v[176:179], v0 offset:3072
	v_add_u32_e32 v0, s68, v141
	ds_read_b128 v[180:183], v0
	ds_read_b128 v[184:187], v0 offset:1024
	ds_read_b128 v[188:191], v0 offset:2048
	ds_read_b128 v[202:205], v0 offset:3072
	s_add_u32 s54, s54, 0x40000
	s_addc_u32 s55, s55, 0
	s_mov_b32 m0, s56
	ds_read_b128 v[206:209], v159 offset:32768
	ds_read_b128 v[210:213], v159 offset:33792
	ds_read_b128 v[214:217], v159 offset:34816
	ds_read_b128 v[218:221], v159 offset:35840
	ds_read_b128 v[222:225], v159 offset:36864
	ds_read_b128 v[226:229], v159 offset:37888
	ds_read_b128 v[230:233], v159 offset:38912
	ds_read_b128 v[234:237], v159 offset:39936
	global_load_lds_dwordx4 v130, s[54:55]
	s_mov_b32 m0, s57
	s_nop 0
	global_load_lds_dwordx4 v134, s[54:55]
	s_waitcnt vmcnt(8)
	s_waitcnt lgkmcnt(0)
	s_barrier
	s_setprio 1
	s_waitcnt lgkmcnt(0)
	v_mfma_f32_16x16x32_bf16 v[126:129], v[150:153], v[206:209], v[126:129]
	v_mfma_f32_16x16x32_bf16 v[118:121], v[172:175], v[206:209], v[118:121]
	v_mfma_f32_16x16x32_bf16 v[110:113], v[150:153], v[214:217], v[110:113]
	v_mfma_f32_16x16x32_bf16 v[102:105], v[172:175], v[214:217], v[102:105]
	v_mfma_f32_16x16x32_bf16 v[94:97], v[150:153], v[222:225], v[94:97]
	v_mfma_f32_16x16x32_bf16 v[86:89], v[172:175], v[222:225], v[86:89]
	v_mfma_f32_16x16x32_bf16 v[78:81], v[150:153], v[230:233], v[78:81]
	v_mfma_f32_16x16x32_bf16 v[70:73], v[172:175], v[230:233], v[70:73]
	v_mfma_f32_16x16x32_bf16 v[126:129], v[154:157], v[210:213], v[126:129]
	v_mfma_f32_16x16x32_bf16 v[118:121], v[176:179], v[210:213], v[118:121]
	v_mfma_f32_16x16x32_bf16 v[110:113], v[154:157], v[218:221], v[110:113]
	v_mfma_f32_16x16x32_bf16 v[102:105], v[176:179], v[218:221], v[102:105]
	v_mfma_f32_16x16x32_bf16 v[94:97], v[154:157], v[226:229], v[94:97]
	v_mfma_f32_16x16x32_bf16 v[86:89], v[176:179], v[226:229], v[86:89]
	v_mfma_f32_16x16x32_bf16 v[78:81], v[154:157], v[234:237], v[78:81]
	v_mfma_f32_16x16x32_bf16 v[70:73], v[176:179], v[234:237], v[70:73]
	s_setprio 0
	s_setprio 1
	v_mfma_f32_16x16x32_bf16 v[122:125], v[180:183], v[206:209], v[122:125]
	v_mfma_f32_16x16x32_bf16 v[114:117], v[188:191], v[206:209], v[114:117]
	v_mfma_f32_16x16x32_bf16 v[106:109], v[180:183], v[214:217], v[106:109]
	v_mfma_f32_16x16x32_bf16 v[98:101], v[188:191], v[214:217], v[98:101]
	v_mfma_f32_16x16x32_bf16 v[90:93], v[180:183], v[222:225], v[90:93]
	v_mfma_f32_16x16x32_bf16 v[82:85], v[188:191], v[222:225], v[82:85]
	v_mfma_f32_16x16x32_bf16 v[74:77], v[180:183], v[230:233], v[74:77]
	v_mfma_f32_16x16x32_bf16 v[66:69], v[188:191], v[230:233], v[66:69]
	v_mfma_f32_16x16x32_bf16 v[122:125], v[184:187], v[210:213], v[122:125]
	v_mfma_f32_16x16x32_bf16 v[114:117], v[202:205], v[210:213], v[114:117]
	v_mfma_f32_16x16x32_bf16 v[106:109], v[184:187], v[218:221], v[106:109]
	v_mfma_f32_16x16x32_bf16 v[98:101], v[202:205], v[218:221], v[98:101]
	v_mfma_f32_16x16x32_bf16 v[90:93], v[184:187], v[226:229], v[90:93]
	v_mfma_f32_16x16x32_bf16 v[82:85], v[202:205], v[226:229], v[82:85]
	v_mfma_f32_16x16x32_bf16 v[74:77], v[184:187], v[234:237], v[74:77]
	v_mfma_f32_16x16x32_bf16 v[66:69], v[202:205], v[234:237], v[66:69]
	s_setprio 0
	s_barrier
; #define PG8_STAGE(bufoff, gbase, voff) do { _Pragma("unroll") for (int _i = 0; _i < 2; ++_i) \
;         __builtin_amdgcn_global_load_lds((const unsigned*)((const char*)(gbase) + (voff)[_i]), (PG8_LAS unsigned*)(lds + (bufoff) + ldsw + _i * 8192), 16, 0, 0); } while (0)
; #define PG8_LDA(dst, b, h) do { _Pragma("unroll") for (int m = 0; m < 4; ++m) _Pragma("unroll") for (int k = 0; k < 2; ++k) dst[m][k] = *(const PG8_LAS bf16x8*)(lds + PG8_SA(b, h) + aoff + m * 2048 + k * 1024); } while (0)
; #define PG8_MMA(ai, bj, At, Bt) do { __builtin_amdgcn_s_setprio(1); _Pragma("unroll") for (int m = 0; m < 4; ++m) _Pragma("unroll") for (int n = 0; n < 2; ++n) _Pragma("unroll") for (int k = 0; k < 2; ++k) \
;         acc[ai][bj][m][n] = __builtin_amdgcn_mfma_f32_16x16x32_bf16(Bt[n][k], At[m][k], acc[ai][bj][m][n], 0, 0, 0); __builtin_amdgcn_s_setprio(0); } while (0)
; #define PG8_WAIT_V(n) asm volatile("s_waitcnt vmcnt(" #n ")" ::: "memory")
; #define PG8_WAIT_L(n) asm volatile("s_waitcnt lgkmcnt(" #n ")" ::: "memory")
; #define PG8_BAR __builtin_amdgcn_s_barrier()
; #define PG8_SCHED __builtin_amdgcn_sched_barrier(0)
; #define PG8_STAGE(bufoff, gbase, voff) do { _Pragma("unroll") for (int _i = 0; _i < 2; ++_i) \
;         __builtin_amdgcn_global_load_lds((const unsigned*)((const char*)(gbase) + (voff)[_i]), (PG8_LAS unsigned*)(lds + (bufoff) + ldsw + _i * 8192), 16, 0, 0); } while (0)
; #define PG8_LDA(dst, b, h) do { _Pragma("unroll") for (int m = 0; m < 4; ++m) _Pragma("unroll") for (int k = 0; k < 2; ++k) dst[m][k] = *(const PG8_LAS bf16x8*)(lds + PG8_SA(b, h) + aoff + m * 2048 + k * 1024); } while (0)
; #define PG8_WAIT_V(n) asm volatile("s_waitcnt vmcnt(" #n ")" ::: "memory")
; #define PG8_WAIT_L(n) asm volatile("s_waitcnt lgkmcnt(" #n ")" ::: "memory")
; #define PG8_BAR __builtin_amdgcn_s_barrier()
; #define PG8_SCHED __builtin_amdgcn_sched_barrier(0)
; template <class Epi, class Sched, bool ALIGN_EPI = false, bool SP2 = false>
; __device__ __forceinline__ void gemm_phase(PG8_LAS unsigned char* lds, const Gemm g, const Sched& S, const Epi& E, const int tid_in) {
;     ...
;             PG8_LDA(At, 1, 1); PG8_STAGE(PG8_SB(1, 0), b3, voffB); PG8_STAGE(PG8_SB(1, 1), b3 + hstep, voffB); PG8_STAGE(PG8_SA(1, 0), a3, voffA);
;             PG8_WAIT_V(8); PG8_WAIT_L(0); PG8_BAR; PG8_MMA(1, 0, At, B0); PG8_MMA(1, 1, At, B1); PG8_BAR; PG8_SCHED;
	s_add_i32 s51, s51, s44
	v_lshl_add_u64 v[238:239], v[238:239], 0, s[82:83]
	s_mov_b32 m0, s51
	ds_read_b128 v[206:209], v159 offset:49152
	ds_read_b128 v[210:213], v159 offset:50176
	ds_read_b128 v[214:217], v159 offset:51200
	ds_read_b128 v[218:221], v159 offset:52224
	ds_read_b128 v[222:225], v159 offset:53248
	ds_read_b128 v[226:229], v159 offset:54272
	ds_read_b128 v[230:233], v159 offset:55296
	ds_read_b128 v[234:237], v159 offset:56320
	global_load_lds_dwordx4 v[238:239], off
	s_add_i32 m0, s51, 0x2000
	s_add_u32 s14, s14, 0x40080
	v_lshl_add_u64 v[238:239], v[240:241], 0, s[82:83]
	s_addc_u32 s15, s15, 0
	s_add_i32 s51, s68, s44
	global_load_lds_dwordx4 v[238:239], off
	s_mov_b32 m0, s51
	s_nop 0
	global_load_lds_dwordx4 v132, s[14:15]
	s_add_i32 m0, s51, 0x2000
	s_nop 0
	global_load_lds_dwordx4 v136, s[14:15]
	v_lshl_add_u64 v[238:239], v[242:243], 0, s[82:83]
	s_mov_b32 m0, s49
	s_nop 0
	global_load_lds_dwordx4 v[238:239], off
	v_lshl_add_u64 v[238:239], v[244:245], 0, s[82:83]
	s_mov_b32 m0, s94
	s_nop 0
	global_load_lds_dwordx4 v[238:239], off
	s_waitcnt vmcnt(8)
	s_waitcnt lgkmcnt(0)
	s_barrier
	s_setprio 1
	s_waitcnt lgkmcnt(0)
	v_mfma_f32_16x16x32_bf16 v[62:65], v[150:153], v[206:209], v[62:65]
	v_mfma_f32_16x16x32_bf16 v[54:57], v[172:175], v[206:209], v[54:57]
	v_mfma_f32_16x16x32_bf16 v[46:49], v[150:153], v[214:217], v[46:49]
	v_mfma_f32_16x16x32_bf16 v[38:41], v[172:175], v[214:217], v[38:41]
	v_mfma_f32_16x16x32_bf16 v[30:33], v[150:153], v[222:225], v[30:33]
	v_mfma_f32_16x16x32_bf16 v[22:25], v[172:175], v[222:225], v[22:25]
	v_mfma_f32_16x16x32_bf16 v[14:17], v[150:153], v[230:233], v[14:17]
	v_mfma_f32_16x16x32_bf16 v[6:9], v[172:175], v[230:233], v[6:9]
	v_mfma_f32_16x16x32_bf16 v[62:65], v[154:157], v[210:213], v[62:65]
	v_mfma_f32_16x16x32_bf16 v[54:57], v[176:179], v[210:213], v[54:57]
	v_mfma_f32_16x16x32_bf16 v[46:49], v[154:157], v[218:221], v[46:49]
	v_mfma_f32_16x16x32_bf16 v[38:41], v[176:179], v[218:221], v[38:41]
	v_mfma_f32_16x16x32_bf16 v[30:33], v[154:157], v[226:229], v[30:33]
	v_mfma_f32_16x16x32_bf16 v[22:25], v[176:179], v[226:229], v[22:25]
	v_mfma_f32_16x16x32_bf16 v[14:17], v[154:157], v[234:237], v[14:17]
	v_mfma_f32_16x16x32_bf16 v[6:9], v[176:179], v[234:237], v[6:9]
	s_setprio 0
	s_setprio 1
	v_mfma_f32_16x16x32_bf16 v[58:61], v[180:183], v[206:209], v[58:61]
	v_mfma_f32_16x16x32_bf16 v[50:53], v[188:191], v[206:209], v[50:53]
	v_mfma_f32_16x16x32_bf16 v[42:45], v[180:183], v[214:217], v[42:45]
	v_mfma_f32_16x16x32_bf16 v[34:37], v[188:191], v[214:217], v[34:37]
	v_mfma_f32_16x16x32_bf16 v[26:29], v[180:183], v[222:225], v[26:29]
	v_mfma_f32_16x16x32_bf16 v[18:21], v[188:191], v[222:225], v[18:21]
	v_mfma_f32_16x16x32_bf16 v[10:13], v[180:183], v[230:233], v[10:13]
	v_mfma_f32_16x16x32_bf16 v[2:5], v[188:191], v[230:233], v[2:5]
	v_mfma_f32_16x16x32_bf16 v[58:61], v[184:187], v[210:213], v[58:61]
	v_mfma_f32_16x16x32_bf16 v[50:53], v[202:205], v[210:213], v[50:53]
	v_mfma_f32_16x16x32_bf16 v[42:45], v[184:187], v[218:221], v[42:45]
	v_mfma_f32_16x16x32_bf16 v[34:37], v[202:205], v[218:221], v[34:37]
	v_mfma_f32_16x16x32_bf16 v[26:29], v[184:187], v[226:229], v[26:29]
	v_mfma_f32_16x16x32_bf16 v[18:21], v[202:205], v[226:229], v[18:21]
	v_mfma_f32_16x16x32_bf16 v[10:13], v[184:187], v[234:237], v[10:13]
	v_mfma_f32_16x16x32_bf16 v[2:5], v[202:205], v[234:237], v[2:5]
	s_setprio 0
	s_barrier
	s_add_i32 vcc_hi, vcc_hi, 2
	s_add_u32 s8, s8, 0x100
	s_addc_u32 s9, s9, 0
	s_add_u32 s91, s91, 0x100
	s_addc_u32 vcc_lo, vcc_lo, 0
	s_cmp_gt_u32 vcc_hi, 13
	s_cbranch_scc0 .LBB0_221
	s_and_b64 vcc, exec, s[72:73]
	s_cbranch_vccz .LBB0_224
	s_barrier
